# barrier / panel-meet spin loops poll without s_sleep
# speedup vs baseline: 1.0204x; 1.0070x over previous
.LBB0_17:
	s_nop 7
	global_load_dword v3, v1, s[2:3] offset:32 sc1
	s_waitcnt vmcnt(0)
	v_and_b32_e32 v3, 0xffff0000, v3
	v_cmp_ne_u32_e32 vcc, v3, v2
	s_or_b64 s[4:5], vcc, s[4:5]
	s_andn2_b64 exec, exec, s[4:5]
	s_cbranch_execnz .LBB0_17

.LBB0_151:
	global_load_dword v16, v17, s[4:5] sc1
	s_waitcnt lgkmcnt(0)
	global_load_dword v1, v17, s[6:7] sc1
	global_load_dword v2, v17, s[8:9] sc1
	global_load_dword v3, v17, s[10:11] sc1
	global_load_dword v4, v17, s[12:13] sc1
	global_load_dword v5, v17, s[14:15] sc1
	global_load_dword v6, v17, s[18:19] sc1
	global_load_dword v7, v17, s[20:21] sc1
	global_load_dword v8, v17, s[22:23] sc1
	global_load_dword v9, v17, s[24:25] sc1
	global_load_dword v10, v17, s[26:27] sc1
	global_load_dword v11, v17, s[28:29] sc1
	global_load_dword v12, v17, s[30:31] sc1
	global_load_dword v13, v17, s[34:35] sc1
	global_load_dword v14, v17, s[38:39] sc1
	global_load_dword v15, v17, s[40:41] sc1
	s_mov_b64 s[42:43], -1
	s_mov_b64 s[46:47], -1
	s_waitcnt vmcnt(14)
	v_add_u32_e32 v18, v1, v16
	s_waitcnt vmcnt(13)
	v_add_u32_e32 v18, v18, v2
	s_waitcnt vmcnt(12)
	v_add_u32_e32 v18, v18, v3
	s_waitcnt vmcnt(11)
	v_add_u32_e32 v18, v18, v4
	s_waitcnt vmcnt(10)
	v_add_u32_e32 v18, v18, v5
	s_waitcnt vmcnt(9)
	v_add_u32_e32 v18, v18, v6
	s_waitcnt vmcnt(8)
	v_add_u32_e32 v18, v18, v7
	s_waitcnt vmcnt(7)
	v_add_u32_e32 v18, v18, v8
	s_waitcnt vmcnt(6)
	v_add_u32_e32 v18, v18, v9
	s_waitcnt vmcnt(5)
	v_add_u32_e32 v18, v18, v10
	s_waitcnt vmcnt(4)
	v_add_u32_e32 v18, v18, v11
	s_waitcnt vmcnt(3)
	v_add_u32_e32 v18, v18, v12
	s_waitcnt vmcnt(2)
	v_add_u32_e32 v18, v18, v13
	s_waitcnt vmcnt(1)
	v_add_u32_e32 v18, v18, v14
	s_waitcnt vmcnt(0)
	v_add_u32_e32 v18, v18, v15
	v_cmp_eq_u32_e32 vcc, s33, v18
	s_cbranch_vccnz .LBB0_150
	s_and_b32 s37, s36, 0xff
	s_cmp_eq_u32 s37, 0
	s_mov_b64 s[48:49], -1
	s_nop 7
	s_cbranch_scc1 .LBB0_155
	s_and_b64 vcc, exec, s[48:49]
	s_cbranch_vccz .LBB0_150

.LBB0_169:
	s_and_b32 s20, s24, 0xff
	s_mov_b64 s[18:19], -1
	s_cmp_lg_u32 s20, 0
	s_mov_b64 s[22:23], -1
	s_nop 7
	s_cbranch_scc0 .LBB0_172
	s_and_b64 vcc, exec, s[22:23]
	s_cbranch_vccz .LBB0_168

.LBB0_186:
	s_and_b32 s18, s24, 0xff
	s_cmp_lg_u32 s18, 0
	s_mov_b64 s[20:21], -1
	s_nop 7
	s_cbranch_scc0 .LBB0_189
	s_mov_b64 s[22:23], -1
	s_and_b64 vcc, exec, s[20:21]
	s_cbranch_vccz .LBB0_185

.LBB0_606:
	global_load_dword v16, v17, s[2:3] sc1
	s_waitcnt lgkmcnt(0)
	global_load_dword v1, v17, s[6:7] sc1
	global_load_dword v2, v17, s[8:9] sc1
	global_load_dword v3, v17, s[10:11] sc1
	global_load_dword v4, v17, s[12:13] sc1
	global_load_dword v5, v17, s[14:15] sc1
	global_load_dword v6, v17, s[16:17] sc1
	global_load_dword v7, v17, s[18:19] sc1
	global_load_dword v8, v17, s[20:21] sc1
	global_load_dword v9, v17, s[22:23] sc1
	global_load_dword v10, v17, s[24:25] sc1
	global_load_dword v11, v17, s[26:27] sc1
	global_load_dword v12, v17, s[28:29] sc1
	global_load_dword v13, v17, s[30:31] sc1
	global_load_dword v14, v17, s[34:35] sc1
	global_load_dword v15, v17, s[38:39] sc1
	s_mov_b64 s[40:41], -1
	s_mov_b64 s[42:43], -1
	s_waitcnt vmcnt(14)
	v_add_u32_e32 v18, v1, v16
	s_waitcnt vmcnt(13)
	v_add_u32_e32 v18, v18, v2
	s_waitcnt vmcnt(12)
	v_add_u32_e32 v18, v18, v3
	s_waitcnt vmcnt(11)
	v_add_u32_e32 v18, v18, v4
	s_waitcnt vmcnt(10)
	v_add_u32_e32 v18, v18, v5
	s_waitcnt vmcnt(9)
	v_add_u32_e32 v18, v18, v6
	s_waitcnt vmcnt(8)
	v_add_u32_e32 v18, v18, v7
	s_waitcnt vmcnt(7)
	v_add_u32_e32 v18, v18, v8
	s_waitcnt vmcnt(6)
	v_add_u32_e32 v18, v18, v9
	s_waitcnt vmcnt(5)
	v_add_u32_e32 v18, v18, v10
	s_waitcnt vmcnt(4)
	v_add_u32_e32 v18, v18, v11
	s_waitcnt vmcnt(3)
	v_add_u32_e32 v18, v18, v12
	s_waitcnt vmcnt(2)
	v_add_u32_e32 v18, v18, v13
	s_waitcnt vmcnt(1)
	v_add_u32_e32 v18, v18, v14
	s_waitcnt vmcnt(0)
	v_add_u32_e32 v18, v18, v15
	v_cmp_eq_u32_e32 vcc, s33, v18
	s_cbranch_vccnz .LBB0_605
	s_and_b32 s37, s36, 0xff
	s_cmp_eq_u32 s37, 0
	s_mov_b64 s[46:47], -1
	s_nop 7
	s_cbranch_scc1 .LBB0_610
	s_and_b64 vcc, exec, s[46:47]
	s_cbranch_vccz .LBB0_605

.LBB0_624:
	s_and_b32 s18, s22, 0xff
	s_mov_b64 s[16:17], -1
	s_cmp_lg_u32 s18, 0
	s_mov_b64 s[20:21], -1
	s_nop 7
	s_cbranch_scc0 .LBB0_627
	s_and_b64 vcc, exec, s[20:21]
	s_cbranch_vccz .LBB0_623

.LBB0_641:
	s_and_b32 s16, s22, 0xff
	s_cmp_lg_u32 s16, 0
	s_mov_b64 s[18:19], -1
	s_nop 7
	s_cbranch_scc0 .LBB0_644
	s_mov_b64 s[20:21], -1
	s_and_b64 vcc, exec, s[18:19]
	s_cbranch_vccz .LBB0_640

.LBB0_912:
	global_load_dword v16, v17, s[4:5] sc1
	s_waitcnt lgkmcnt(0)
	global_load_dword v1, v17, s[6:7] sc1
	global_load_dword v2, v17, s[8:9] sc1
	global_load_dword v3, v17, s[10:11] sc1
	global_load_dword v4, v17, s[12:13] sc1
	global_load_dword v5, v17, s[16:17] sc1
	global_load_dword v6, v17, s[18:19] sc1
	global_load_dword v7, v17, s[20:21] sc1
	global_load_dword v8, v17, s[22:23] sc1
	global_load_dword v9, v17, s[24:25] sc1
	global_load_dword v10, v17, s[26:27] sc1
	global_load_dword v11, v17, s[28:29] sc1
	global_load_dword v12, v17, s[30:31] sc1
	global_load_dword v13, v17, s[34:35] sc1
	global_load_dword v14, v17, s[38:39] sc1
	global_load_dword v15, v17, s[40:41] sc1
	s_mov_b64 s[42:43], -1
	s_mov_b64 s[44:45], -1
	s_waitcnt vmcnt(14)
	v_add_u32_e32 v18, v1, v16
	s_waitcnt vmcnt(13)
	v_add_u32_e32 v18, v18, v2
	s_waitcnt vmcnt(12)
	v_add_u32_e32 v18, v18, v3
	s_waitcnt vmcnt(11)
	v_add_u32_e32 v18, v18, v4
	s_waitcnt vmcnt(10)
	v_add_u32_e32 v18, v18, v5
	s_waitcnt vmcnt(9)
	v_add_u32_e32 v18, v18, v6
	s_waitcnt vmcnt(8)
	v_add_u32_e32 v18, v18, v7
	s_waitcnt vmcnt(7)
	v_add_u32_e32 v18, v18, v8
	s_waitcnt vmcnt(6)
	v_add_u32_e32 v18, v18, v9
	s_waitcnt vmcnt(5)
	v_add_u32_e32 v18, v18, v10
	s_waitcnt vmcnt(4)
	v_add_u32_e32 v18, v18, v11
	s_waitcnt vmcnt(3)
	v_add_u32_e32 v18, v18, v12
	s_waitcnt vmcnt(2)
	v_add_u32_e32 v18, v18, v13
	s_waitcnt vmcnt(1)
	v_add_u32_e32 v18, v18, v14
	s_waitcnt vmcnt(0)
	v_add_u32_e32 v18, v18, v15
	v_cmp_eq_u32_e32 vcc, s33, v18
	s_cbranch_vccnz .LBB0_911
	s_and_b32 s37, s36, 0xff
	s_cmp_eq_u32 s37, 0
	s_mov_b64 s[46:47], -1
	s_nop 7
	s_cbranch_scc1 .LBB0_916
	s_and_b64 vcc, exec, s[46:47]
	s_cbranch_vccz .LBB0_911

.LBB0_1029:
	global_load_dword v16, v17, s[4:5] sc1
	s_waitcnt lgkmcnt(0)
	global_load_dword v1, v17, s[6:7] sc1
	global_load_dword v2, v17, s[8:9] sc1
	global_load_dword v3, v17, s[14:15] sc1
	global_load_dword v4, v17, s[18:19] sc1
	global_load_dword v5, v17, s[20:21] sc1
	global_load_dword v6, v17, s[22:23] sc1
	global_load_dword v7, v17, s[24:25] sc1
	global_load_dword v8, v17, s[26:27] sc1
	global_load_dword v9, v17, s[28:29] sc1
	global_load_dword v10, v17, s[30:31] sc1
	global_load_dword v11, v17, s[34:35] sc1
	global_load_dword v12, v17, s[38:39] sc1
	global_load_dword v13, v17, s[40:41] sc1
	global_load_dword v14, v17, s[42:43] sc1
	global_load_dword v15, v17, s[44:45] sc1
	s_mov_b64 s[46:47], -1
	s_mov_b64 s[48:49], -1
	s_waitcnt vmcnt(14)
	v_add_u32_e32 v18, v1, v16
	s_waitcnt vmcnt(13)
	v_add_u32_e32 v18, v18, v2
	s_waitcnt vmcnt(12)
	v_add_u32_e32 v18, v18, v3
	s_waitcnt vmcnt(11)
	v_add_u32_e32 v18, v18, v4
	s_waitcnt vmcnt(10)
	v_add_u32_e32 v18, v18, v5
	s_waitcnt vmcnt(9)
	v_add_u32_e32 v18, v18, v6
	s_waitcnt vmcnt(8)
	v_add_u32_e32 v18, v18, v7
	s_waitcnt vmcnt(7)
	v_add_u32_e32 v18, v18, v8
	s_waitcnt vmcnt(6)
	v_add_u32_e32 v18, v18, v9
	s_waitcnt vmcnt(5)
	v_add_u32_e32 v18, v18, v10
	s_waitcnt vmcnt(4)
	v_add_u32_e32 v18, v18, v11
	s_waitcnt vmcnt(3)
	v_add_u32_e32 v18, v18, v12
	s_waitcnt vmcnt(2)
	v_add_u32_e32 v18, v18, v13
	s_waitcnt vmcnt(1)
	v_add_u32_e32 v18, v18, v14
	s_waitcnt vmcnt(0)
	v_add_u32_e32 v18, v18, v15
	v_cmp_eq_u32_e32 vcc, s33, v18
	s_cbranch_vccnz .LBB0_1028
	s_and_b32 s37, s36, 0xff
	s_cmp_eq_u32 s37, 0
	s_mov_b64 s[50:51], -1
	s_nop 7
	s_cbranch_scc1 .LBB0_1033
	s_and_b64 vcc, exec, s[50:51]
	s_cbranch_vccz .LBB0_1028

.LBB0_1047:
	s_and_b32 s24, s28, 0xff
	s_mov_b64 s[22:23], -1
	s_cmp_lg_u32 s24, 0
	s_mov_b64 s[26:27], -1
	s_nop 7
	s_cbranch_scc0 .LBB0_1050
	s_and_b64 vcc, exec, s[26:27]
	s_cbranch_vccz .LBB0_1046

.LBB0_1064:
	s_and_b32 s22, s28, 0xff
	s_cmp_lg_u32 s22, 0
	s_mov_b64 s[24:25], -1
	s_nop 7
	s_cbranch_scc0 .LBB0_1067
	s_mov_b64 s[26:27], -1
	s_and_b64 vcc, exec, s[24:25]
	s_cbranch_vccz .LBB0_1063

.LBB0_1118:
	global_load_dword v16, v17, s[4:5] sc1
	s_waitcnt lgkmcnt(0)
	global_load_dword v1, v17, s[6:7] sc1
	global_load_dword v2, v17, s[8:9] sc1
	global_load_dword v3, v17, s[10:11] sc1
	global_load_dword v4, v17, s[18:19] sc1
	global_load_dword v5, v17, s[20:21] sc1
	global_load_dword v6, v17, s[22:23] sc1
	global_load_dword v7, v17, s[24:25] sc1
	global_load_dword v8, v17, s[26:27] sc1
	global_load_dword v9, v17, s[28:29] sc1
	global_load_dword v10, v17, s[30:31] sc1
	global_load_dword v11, v17, s[34:35] sc1
	global_load_dword v12, v17, s[38:39] sc1
	global_load_dword v13, v17, s[40:41] sc1
	global_load_dword v14, v17, s[42:43] sc1
	global_load_dword v15, v17, s[44:45] sc1
	s_mov_b64 s[46:47], -1
	s_mov_b64 s[48:49], -1
	s_waitcnt vmcnt(14)
	v_add_u32_e32 v18, v1, v16
	s_waitcnt vmcnt(13)
	v_add_u32_e32 v18, v18, v2
	s_waitcnt vmcnt(12)
	v_add_u32_e32 v18, v18, v3
	s_waitcnt vmcnt(11)
	v_add_u32_e32 v18, v18, v4
	s_waitcnt vmcnt(10)
	v_add_u32_e32 v18, v18, v5
	s_waitcnt vmcnt(9)
	v_add_u32_e32 v18, v18, v6
	s_waitcnt vmcnt(8)
	v_add_u32_e32 v18, v18, v7
	s_waitcnt vmcnt(7)
	v_add_u32_e32 v18, v18, v8
	s_waitcnt vmcnt(6)
	v_add_u32_e32 v18, v18, v9
	s_waitcnt vmcnt(5)
	v_add_u32_e32 v18, v18, v10
	s_waitcnt vmcnt(4)
	v_add_u32_e32 v18, v18, v11
	s_waitcnt vmcnt(3)
	v_add_u32_e32 v18, v18, v12
	s_waitcnt vmcnt(2)
	v_add_u32_e32 v18, v18, v13
	s_waitcnt vmcnt(1)
	v_add_u32_e32 v18, v18, v14
	s_waitcnt vmcnt(0)
	v_add_u32_e32 v18, v18, v15
	v_cmp_eq_u32_e32 vcc, s33, v18
	s_cbranch_vccnz .LBB0_1117
	s_and_b32 s37, s36, 0xff
	s_cmp_eq_u32 s37, 0
	s_mov_b64 s[50:51], -1
	s_nop 7
	s_cbranch_scc1 .LBB0_1122
	s_and_b64 vcc, exec, s[50:51]
	s_cbranch_vccz .LBB0_1117

.LBB0_1296:
	global_load_dword v3, v2, s[2:3] sc1
	s_mov_b64 s[4:5], -1
	s_waitcnt vmcnt(0)
	v_cmp_lt_u32_e32 vcc, 3, v3
	s_cbranch_vccnz .LBB0_1295
	s_cmp_lg_u32 s6, 0
	s_nop 7
	s_cbranch_scc0 .LBB0_1294
	global_load_dword v3, v2, s[2:3] sc1
	s_waitcnt vmcnt(0)
	v_cmp_gt_u32_e32 vcc, 4, v3
	s_cbranch_vccz .LBB0_1295
	s_nop 7
	global_load_dword v3, v2, s[2:3] sc1
	s_waitcnt vmcnt(0)
	v_cmp_gt_u32_e32 vcc, 4, v3
	s_cbranch_vccz .LBB0_1295
	s_nop 7
	global_load_dword v3, v2, s[2:3] sc1
	s_waitcnt vmcnt(0)
	v_cmp_gt_u32_e32 vcc, 4, v3
	s_cbranch_vccz .LBB0_1295
	s_nop 7
	global_load_dword v3, v2, s[2:3] sc1
	s_waitcnt vmcnt(0)
	v_cmp_gt_u32_e32 vcc, 4, v3
	s_cbranch_vccz .LBB0_1295
	s_nop 7
	global_load_dword v3, v2, s[2:3] sc1
	s_waitcnt vmcnt(0)
	v_cmp_gt_u32_e32 vcc, 4, v3
	s_cbranch_vccz .LBB0_1295
	s_nop 7
	global_load_dword v3, v2, s[2:3] sc1
	s_waitcnt vmcnt(0)
	v_cmp_gt_u32_e32 vcc, 4, v3
	s_cbranch_vccz .LBB0_1295
	s_nop 7
	global_load_dword v3, v2, s[2:3] sc1
	s_waitcnt vmcnt(0)
	v_cmp_gt_u32_e32 vcc, 4, v3
	s_cbranch_vccz .LBB0_1295
	s_nop 7
	s_add_i32 s6, s6, -8
	s_mov_b64 s[4:5], 0
	s_branch .LBB0_1295

.LBB0_1316:
	global_load_dword v13, v3, s[2:3] sc1
	s_mov_b64 s[4:5], -1
	s_waitcnt vmcnt(0)
	v_cmp_lt_u32_e32 vcc, 15, v13
	s_cbranch_vccnz .LBB0_1315
	s_cmp_lg_u32 s6, 0
	s_nop 7
	s_cbranch_scc0 .LBB0_1314
	global_load_dword v13, v3, s[2:3] sc1
	s_waitcnt vmcnt(0)
	v_cmp_gt_u32_e32 vcc, 16, v13
	s_cbranch_vccz .LBB0_1315
	s_nop 7
	global_load_dword v13, v3, s[2:3] sc1
	s_waitcnt vmcnt(0)
	v_cmp_gt_u32_e32 vcc, 16, v13
	s_cbranch_vccz .LBB0_1315
	s_nop 7
	global_load_dword v13, v3, s[2:3] sc1
	s_waitcnt vmcnt(0)
	v_cmp_gt_u32_e32 vcc, 16, v13
	s_cbranch_vccz .LBB0_1315
	s_nop 7
	global_load_dword v13, v3, s[2:3] sc1
	s_waitcnt vmcnt(0)
	v_cmp_gt_u32_e32 vcc, 16, v13
	s_cbranch_vccz .LBB0_1315
	s_nop 7
	global_load_dword v13, v3, s[2:3] sc1
	s_waitcnt vmcnt(0)
	v_cmp_gt_u32_e32 vcc, 16, v13
	s_cbranch_vccz .LBB0_1315
	s_nop 7
	global_load_dword v13, v3, s[2:3] sc1
	s_waitcnt vmcnt(0)
	v_cmp_gt_u32_e32 vcc, 16, v13
	s_cbranch_vccz .LBB0_1315
	s_nop 7
	global_load_dword v13, v3, s[2:3] sc1
	s_waitcnt vmcnt(0)
	v_cmp_gt_u32_e32 vcc, 16, v13
	s_cbranch_vccz .LBB0_1315
	s_nop 7
	s_add_i32 s6, s6, -8
	s_mov_b64 s[4:5], 0
	s_branch .LBB0_1315

.LBB0_1335:
	global_load_dword v16, v17, s[4:5] sc1
	s_waitcnt lgkmcnt(0)
	global_load_dword v1, v17, s[6:7] sc1
	global_load_dword v2, v17, s[8:9] sc1
	global_load_dword v3, v17, s[10:11] sc1
	global_load_dword v4, v17, s[12:13] sc1
	global_load_dword v5, v17, s[16:17] sc1
	global_load_dword v6, v17, s[18:19] sc1
	global_load_dword v7, v17, s[20:21] sc1
	global_load_dword v8, v17, s[22:23] sc1
	global_load_dword v9, v17, s[24:25] sc1
	global_load_dword v10, v17, s[26:27] sc1
	global_load_dword v11, v17, s[28:29] sc1
	global_load_dword v12, v17, s[30:31] sc1
	global_load_dword v13, v17, s[34:35] sc1
	global_load_dword v14, v17, s[36:37] sc1
	global_load_dword v15, v17, s[38:39] sc1
	s_mov_b64 s[40:41], -1
	s_mov_b64 s[42:43], -1
	s_waitcnt vmcnt(14)
	v_add_u32_e32 v18, v1, v16
	s_waitcnt vmcnt(13)
	v_add_u32_e32 v18, v18, v2
	s_waitcnt vmcnt(12)
	v_add_u32_e32 v18, v18, v3
	s_waitcnt vmcnt(11)
	v_add_u32_e32 v18, v18, v4
	s_waitcnt vmcnt(10)
	v_add_u32_e32 v18, v18, v5
	s_waitcnt vmcnt(9)
	v_add_u32_e32 v18, v18, v6
	s_waitcnt vmcnt(8)
	v_add_u32_e32 v18, v18, v7
	s_waitcnt vmcnt(7)
	v_add_u32_e32 v18, v18, v8
	s_waitcnt vmcnt(6)
	v_add_u32_e32 v18, v18, v9
	s_waitcnt vmcnt(5)
	v_add_u32_e32 v18, v18, v10
	s_waitcnt vmcnt(4)
	v_add_u32_e32 v18, v18, v11
	s_waitcnt vmcnt(3)
	v_add_u32_e32 v18, v18, v12
	s_waitcnt vmcnt(2)
	v_add_u32_e32 v18, v18, v13
	s_waitcnt vmcnt(1)
	v_add_u32_e32 v18, v18, v14
	s_waitcnt vmcnt(0)
	v_add_u32_e32 v18, v18, v15
	v_cmp_eq_u32_e32 vcc, s33, v18
	s_cbranch_vccnz .LBB0_1334
	s_and_b32 s40, s46, 0xff
	s_cmp_eq_u32 s40, 0
	s_mov_b64 s[40:41], -1
	s_mov_b64 s[44:45], -1
	s_nop 7
	s_cbranch_scc1 .LBB0_1339
	s_and_b64 vcc, exec, s[44:45]
	s_cbranch_vccz .LBB0_1334

.LBB0_1370:
	s_and_b32 s18, s24, 0xff
	s_cmp_lg_u32 s18, 0
	s_mov_b64 s[20:21], -1
	s_nop 7
	s_cbranch_scc1 .LBB0_1373
	global_load_dword v2, v1, s[8:9] sc1
	s_waitcnt vmcnt(0)
	v_cmp_eq_u32_e32 vcc, 0, v2
	s_cbranch_vccnz .LBB0_1375
	s_mov_b64 s[20:21], 0
	s_mov_b64 s[18:19], -1

.LBB0_1393:
	s_nop 7
	global_load_dword v2, v0, s[2:3] offset:32 sc1
	s_waitcnt vmcnt(0)
	v_and_b32_e32 v2, 0xffff0000, v2
	v_cmp_ne_u32_e32 vcc, v2, v1
	s_or_b64 s[4:5], vcc, s[4:5]
	s_andn2_b64 exec, exec, s[4:5]
	s_cbranch_execnz .LBB0_1393
